# ffn_in epilogue sample path: touch the later state_ffn rows up front so the serialized per-row-group loads hit L2
# baseline (speedup 1.0000x reference)
.LBB0_1104:
	s_and_b64 vcc, exec, s[0:1]
	s_cbranch_vccz .LBB0_1082
	v_add_u32_e32 v124, s57, v207
	v_readlane_b32 s0, v248, 2
	v_lshlrev_b32_e32 v125, 1, v124
	v_readlane_b32 s10, v248, 12
	v_readlane_b32 s11, v248, 13
	v_ashrrev_i32_e32 v201, 31, v200
	v_readlane_b32 s1, v248, 3
	v_mov_b64_e32 v[102:103], s[10:11]
	v_or_b32_e32 v98, 1, v125
	v_lshlrev_b64 v[90:91], 2, v[200:201]
	v_mad_i64_i32 v[76:77], s[0:1], v98, s69, v[102:103]
	v_lshl_add_u64 v[82:83], s[84:85], 0, v[90:91]
	v_lshl_add_u64 v[70:71], s[28:29], 0, v[90:91]
	v_mad_i64_i32 v[74:75], s[0:1], v125, s69, v[102:103]
	v_lshl_add_u64 v[84:85], v[76:77], 0, v[90:91]
	global_load_dwordx4 v[66:69], v[82:83], off
	s_nop 0
	global_load_dwordx4 v[70:73], v[70:71], off
	v_lshl_add_u64 v[88:89], v[74:75], 0, v[90:91]
	global_load_dwordx4 v[110:113], v[84:85], off
	global_load_dwordx4 v[114:117], v[88:89], off
	v_lshl_add_u64 v[74:75], s[30:31], 0, v[90:91]
	global_load_dwordx4 v[74:77], v[74:75], off
	v_lshl_add_u64 v[86:87], s[86:87], 0, v[90:91]
	global_load_dwordx4 v[78:81], v[86:87], off
	v_add_co_u32_e32 v132, vcc, 0x58000, v88
	s_nop 1
	v_addc_co_u32_e32 v133, vcc, 0, v89, vcc
	global_load_dword v134, v[132:133], off
	v_add_co_u32_e32 v132, vcc, 0x58000, v84
	s_nop 1
	v_addc_co_u32_e32 v133, vcc, 0, v85, vcc
	global_load_dword v134, v[132:133], off
	v_add_co_u32_e32 v132, vcc, 0xb0000, v88
	s_nop 1
	v_addc_co_u32_e32 v133, vcc, 0, v89, vcc
	global_load_dword v134, v[132:133], off
	v_add_co_u32_e32 v132, vcc, 0xb0000, v84
	s_nop 1
	v_addc_co_u32_e32 v133, vcc, 0, v85, vcc
	global_load_dword v134, v[132:133], off
	v_add_co_u32_e32 v132, vcc, 0x108000, v88
	s_nop 1
	v_addc_co_u32_e32 v133, vcc, 0, v89, vcc
	global_load_dword v134, v[132:133], off
	v_add_co_u32_e32 v132, vcc, 0x108000, v84
	s_nop 1
	v_addc_co_u32_e32 v133, vcc, 0, v85, vcc
	global_load_dword v134, v[132:133], off
	v_mov_b64_e32 v[104:105], s[20:21]
	v_mad_i64_i32 v[98:99], s[0:1], v98, s69, v[104:105]
	v_mad_i64_i32 v[92:93], s[0:1], v125, s69, v[104:105]
	v_lshl_add_u64 v[98:99], v[98:99], 0, v[90:91]
	v_mov_b64_e32 v[106:107], s[88:89]
	v_add_u32_e32 v94, 0x4000, v124
	v_lshl_add_u64 v[96:97], v[92:93], 0, v[90:91]
	v_lshlrev_b64 v[108:109], 1, v[200:201]
	v_mad_i64_i32 v[94:95], s[0:1], v94, s70, v[106:107]
	v_add_u32_e32 v123, 33, v125
	v_add_u32_e32 v122, 32, v125
	v_lshl_add_u64 v[92:93], v[94:95], 0, v[108:109]
	v_mad_i64_i32 v[94:95], s[0:1], v123, s69, v[102:103]
	v_mad_i64_i32 v[100:101], s[0:1], v122, s69, v[102:103]
	v_lshl_add_u64 v[94:95], v[94:95], 0, v[90:91]
	v_add_u32_e32 v127, 0x41, v125
	v_add_u32_e32 v126, 64, v125
	v_add_u32_e32 v128, 0x60, v125
	v_add_u32_e32 v125, 0x61, v125
	v_readlane_b32 s2, v248, 4
	s_movk_i32 s2, 0x2000
	v_readlane_b32 s3, v248, 5
	s_movk_i32 s3, 0x5000
	v_readlane_b32 s4, v248, 6
	v_readlane_b32 s5, v248, 7
	v_readlane_b32 s6, v248, 8
	v_readlane_b32 s7, v248, 9
	v_readlane_b32 s8, v248, 10
	v_readlane_b32 s9, v248, 11
	v_readlane_b32 s12, v248, 14
	v_readlane_b32 s13, v248, 15
	v_readlane_b32 s14, v248, 16
	v_readlane_b32 s15, v248, 17
	global_store_dwordx4 v[98:99], v[62:65], off
	s_waitcnt vmcnt(0)
	global_store_dwordx4 v[96:97], v[110:113], off
	v_pk_mul_f32 v[118:119], v[72:73], v[112:113]
	v_pk_mul_f32 v[120:121], v[70:71], v[110:111]
	v_pk_fma_f32 v[116:117], v[68:69], v[116:117], v[118:119]
	v_pk_fma_f32 v[114:115], v[66:67], v[114:115], v[120:121]
	v_pk_fma_f32 v[116:117], v[64:65], v[76:77], v[116:117]
	v_pk_fma_f32 v[114:115], v[62:63], v[74:75], v[114:115]
	v_pk_add_f32 v[116:117], v[80:81], v[116:117]
	v_pk_add_f32 v[114:115], v[78:79], v[114:115]
	v_mul_f32_e32 v120, 0xbfb8aa3b, v116
	v_mul_f32_e32 v118, 0xbfb8aa3b, v114
	v_mul_f32_e32 v119, 0xbfb8aa3b, v115
	v_mul_f32_e32 v121, 0xbfb8aa3b, v117
	v_exp_f32_e32 v118, v118
	v_exp_f32_e32 v119, v119
	v_exp_f32_e32 v120, v120
	v_exp_f32_e32 v121, v121
	v_add_f32_e32 v118, 1.0, v118
	v_add_f32_e32 v119, 1.0, v119
	v_add_f32_e32 v120, 1.0, v120
	v_add_f32_e32 v121, 1.0, v121
	v_rcp_f32_e32 v118, v118
	v_rcp_f32_e32 v119, v119
	v_rcp_f32_e32 v120, v120
	v_rcp_f32_e32 v121, v121
	v_pk_mul_f32 v[62:63], v[114:115], v[118:119]
	s_nop 0
	v_pk_mul_f32 v[58:59], v[58:59], v[62:63]
	v_pk_mul_f32 v[64:65], v[116:117], v[120:121]
	v_cvt_pk_bf16_f32 v58, v58, v59
	v_pk_mul_f32 v[60:61], v[60:61], v[64:65]
	v_mad_i64_i32 v[62:63], s[0:1], v122, s69, v[104:105]
	v_cvt_pk_bf16_f32 v59, v60, v61
	global_store_dwordx2 v[92:93], v[58:59], off
	global_load_dwordx4 v[110:113], v[94:95], off
	v_lshl_add_u64 v[58:59], v[100:101], 0, v[90:91]
	global_load_dwordx4 v[114:117], v[58:59], off
	v_mad_i64_i32 v[120:121], s[0:1], v127, s69, v[102:103]
	v_mad_i64_i32 v[100:101], s[0:1], v123, s69, v[104:105]
	v_lshl_add_u64 v[64:65], v[62:63], 0, v[90:91]
	v_lshl_add_u64 v[62:63], v[120:121], 0, v[90:91]
	v_lshl_add_u64 v[100:101], v[100:101], 0, v[90:91]
	v_add_u32_e32 v60, 0x4010, v124
	v_mad_i64_i32 v[60:61], s[0:1], v60, s70, v[106:107]
	v_lshl_add_u64 v[60:61], v[60:61], 0, v[108:109]
	v_mad_i64_i32 v[118:119], s[0:1], v126, s69, v[102:103]
	global_store_dwordx4 v[100:101], v[54:57], off
	s_waitcnt vmcnt(0)
	global_store_dwordx4 v[64:65], v[110:113], off
	v_pk_mul_f32 v[120:121], v[72:73], v[112:113]
	v_pk_mul_f32 v[122:123], v[70:71], v[110:111]
	v_pk_fma_f32 v[116:117], v[68:69], v[116:117], v[120:121]
	v_pk_fma_f32 v[114:115], v[66:67], v[114:115], v[122:123]
	v_pk_fma_f32 v[116:117], v[56:57], v[76:77], v[116:117]
	v_pk_fma_f32 v[114:115], v[54:55], v[74:75], v[114:115]
	v_pk_add_f32 v[116:117], v[80:81], v[116:117]
	v_pk_add_f32 v[114:115], v[78:79], v[114:115]
	v_mul_f32_e32 v122, 0xbfb8aa3b, v116
	v_mul_f32_e32 v120, 0xbfb8aa3b, v114
	v_mul_f32_e32 v121, 0xbfb8aa3b, v115
	v_mul_f32_e32 v123, 0xbfb8aa3b, v117
	v_exp_f32_e32 v120, v120
	v_exp_f32_e32 v121, v121
	v_exp_f32_e32 v122, v122
	v_exp_f32_e32 v123, v123
	v_add_f32_e32 v120, 1.0, v120
	v_add_f32_e32 v121, 1.0, v121
	v_add_f32_e32 v122, 1.0, v122
	v_add_f32_e32 v123, 1.0, v123
	v_rcp_f32_e32 v120, v120
	v_rcp_f32_e32 v121, v121
	v_rcp_f32_e32 v122, v122
	v_rcp_f32_e32 v123, v123
	v_pk_mul_f32 v[54:55], v[114:115], v[120:121]
	s_nop 0
	v_pk_mul_f32 v[50:51], v[50:51], v[54:55]
	v_pk_mul_f32 v[56:57], v[116:117], v[122:123]
	v_cvt_pk_bf16_f32 v50, v50, v51
	v_pk_mul_f32 v[52:53], v[52:53], v[56:57]
	v_mad_i64_i32 v[54:55], s[0:1], v126, s69, v[104:105]
	v_cvt_pk_bf16_f32 v51, v52, v53
	global_store_dwordx2 v[60:61], v[50:51], off
	global_load_dwordx4 v[110:113], v[62:63], off
	v_lshl_add_u64 v[50:51], v[118:119], 0, v[90:91]
	global_load_dwordx4 v[114:117], v[50:51], off
	v_mad_i64_i32 v[118:119], s[0:1], v127, s69, v[104:105]
	v_mad_i64_i32 v[122:123], s[0:1], v125, s69, v[102:103]
	v_mad_i64_i32 v[120:121], s[0:1], v128, s69, v[102:103]
	v_lshl_add_u64 v[56:57], v[54:55], 0, v[90:91]
	v_lshl_add_u64 v[102:103], v[118:119], 0, v[90:91]
	v_lshl_add_u64 v[54:55], v[122:123], 0, v[90:91]
	v_add_u32_e32 v52, 0x4020, v124
	v_mad_i64_i32 v[52:53], s[0:1], v52, s70, v[106:107]
	v_lshl_add_u64 v[52:53], v[52:53], 0, v[108:109]
	global_store_dwordx4 v[102:103], v[46:49], off
	s_waitcnt vmcnt(0)
	global_store_dwordx4 v[56:57], v[110:113], off
	v_pk_mul_f32 v[118:119], v[72:73], v[112:113]
	v_pk_mul_f32 v[122:123], v[70:71], v[110:111]
	v_pk_fma_f32 v[116:117], v[68:69], v[116:117], v[118:119]
	v_pk_fma_f32 v[114:115], v[66:67], v[114:115], v[122:123]
	v_pk_fma_f32 v[116:117], v[48:49], v[76:77], v[116:117]
	v_pk_fma_f32 v[114:115], v[46:47], v[74:75], v[114:115]
	v_pk_add_f32 v[116:117], v[80:81], v[116:117]
	v_pk_add_f32 v[114:115], v[78:79], v[114:115]
	v_mul_f32_e32 v122, 0xbfb8aa3b, v116
	v_mul_f32_e32 v118, 0xbfb8aa3b, v114
	v_mul_f32_e32 v119, 0xbfb8aa3b, v115
	v_mul_f32_e32 v123, 0xbfb8aa3b, v117
	v_exp_f32_e32 v118, v118
	v_exp_f32_e32 v119, v119
	v_exp_f32_e32 v122, v122
	v_exp_f32_e32 v123, v123
	v_add_f32_e32 v118, 1.0, v118
	v_add_f32_e32 v119, 1.0, v119
	v_add_f32_e32 v122, 1.0, v122
	v_add_f32_e32 v123, 1.0, v123
	v_rcp_f32_e32 v118, v118
	v_rcp_f32_e32 v119, v119
	v_rcp_f32_e32 v122, v122
	v_rcp_f32_e32 v123, v123
	v_pk_mul_f32 v[46:47], v[114:115], v[118:119]
	s_nop 0
	v_pk_mul_f32 v[42:43], v[42:43], v[46:47]
	v_pk_mul_f32 v[48:49], v[116:117], v[122:123]
	v_cvt_pk_bf16_f32 v42, v42, v43
	v_pk_mul_f32 v[44:45], v[44:45], v[48:49]
	v_mad_i64_i32 v[46:47], s[0:1], v128, s69, v[104:105]
	v_cvt_pk_bf16_f32 v43, v44, v45
	global_store_dwordx2 v[52:53], v[42:43], off
	global_load_dwordx4 v[110:113], v[54:55], off
	v_lshl_add_u64 v[42:43], v[120:121], 0, v[90:91]
	global_load_dwordx4 v[114:117], v[42:43], off
	v_mad_i64_i32 v[104:105], s[0:1], v125, s69, v[104:105]
	v_lshl_add_u64 v[48:49], v[46:47], 0, v[90:91]
	v_lshl_add_u64 v[46:47], v[104:105], 0, v[90:91]
	v_add_u32_e32 v44, 0x4030, v124
	v_mad_i64_i32 v[44:45], s[0:1], v44, s70, v[106:107]
	v_lshl_add_u64 v[44:45], v[44:45], 0, v[108:109]
	v_add_co_u32_e32 v106, vcc, s2, v82
	global_store_dwordx4 v[46:47], v[38:41], off
	s_waitcnt vmcnt(0)
	global_store_dwordx4 v[48:49], v[110:113], off
	v_pk_mul_f32 v[72:73], v[72:73], v[112:113]
	v_pk_mul_f32 v[70:71], v[70:71], v[110:111]
	v_pk_fma_f32 v[68:69], v[68:69], v[116:117], v[72:73]
	v_pk_fma_f32 v[66:67], v[66:67], v[114:115], v[70:71]
	v_pk_fma_f32 v[68:69], v[40:41], v[76:77], v[68:69]
	v_pk_fma_f32 v[66:67], v[38:39], v[74:75], v[66:67]
	v_pk_add_f32 v[68:69], v[80:81], v[68:69]
	v_pk_add_f32 v[66:67], v[78:79], v[66:67]
	v_mul_f32_e32 v72, 0xbfb8aa3b, v68
	v_mul_f32_e32 v70, 0xbfb8aa3b, v66
	v_mul_f32_e32 v71, 0xbfb8aa3b, v67
	v_mul_f32_e32 v73, 0xbfb8aa3b, v69
	v_exp_f32_e32 v70, v70
	v_exp_f32_e32 v71, v71
	v_exp_f32_e32 v72, v72
	v_exp_f32_e32 v73, v73
	v_add_f32_e32 v70, 1.0, v70
	v_add_f32_e32 v71, 1.0, v71
	v_add_f32_e32 v72, 1.0, v72
	v_add_f32_e32 v73, 1.0, v73
	v_rcp_f32_e32 v70, v70
	v_rcp_f32_e32 v71, v71
	v_rcp_f32_e32 v72, v72
	v_rcp_f32_e32 v73, v73
	v_addc_co_u32_e32 v107, vcc, 0, v83, vcc
	v_pk_mul_f32 v[38:39], v[66:67], v[70:71]
	v_pk_mul_f32 v[40:41], v[68:69], v[72:73]
	v_pk_mul_f32 v[34:35], v[34:35], v[38:39]
	v_pk_mul_f32 v[36:37], v[36:37], v[40:41]
	v_cvt_pk_bf16_f32 v34, v34, v35
	v_cvt_pk_bf16_f32 v35, v36, v37
	global_store_dwordx2 v[44:45], v[34:35], off
	global_load_dwordx4 v[34:37], v[82:83], off offset:16
	s_nop 0
	global_load_dwordx4 v[38:41], v[106:107], off offset:3088
	global_load_dwordx4 v[66:69], v[88:89], off offset:16
	global_load_dwordx4 v[70:73], v[84:85], off offset:16
	v_add_co_u32_e32 v74, vcc, s3, v82
	s_waitcnt vmcnt(0)
	v_pk_mul_f32 v[84:85], v[38:39], v[70:71]
	v_addc_co_u32_e32 v75, vcc, 0, v83, vcc
	global_load_dwordx4 v[74:77], v[74:75], off offset:2064
	s_nop 0
	global_load_dwordx4 v[78:81], v[86:87], off offset:16
	v_pk_mul_f32 v[82:83], v[40:41], v[72:73]
	v_pk_fma_f32 v[66:67], v[34:35], v[66:67], v[84:85]
	v_pk_fma_f32 v[68:69], v[36:37], v[68:69], v[82:83]
	global_store_dwordx4 v[98:99], v[30:33], off offset:16
	global_store_dwordx4 v[96:97], v[70:73], off offset:16
	s_waitcnt vmcnt(0)
	v_pk_fma_f32 v[68:69], v[32:33], v[76:77], v[68:69]
	v_pk_fma_f32 v[66:67], v[30:31], v[74:75], v[66:67]
	v_pk_add_f32 v[68:69], v[80:81], v[68:69]
	v_pk_add_f32 v[66:67], v[78:79], v[66:67]
	v_mul_f32_e32 v84, 0xbfb8aa3b, v68
	v_mul_f32_e32 v82, 0xbfb8aa3b, v66
	v_mul_f32_e32 v83, 0xbfb8aa3b, v67
	v_mul_f32_e32 v85, 0xbfb8aa3b, v69
	v_exp_f32_e32 v82, v82
	v_exp_f32_e32 v83, v83
	v_exp_f32_e32 v84, v84
	v_exp_f32_e32 v85, v85
	v_add_f32_e32 v82, 1.0, v82
	v_add_f32_e32 v83, 1.0, v83
	v_add_f32_e32 v84, 1.0, v84
	v_add_f32_e32 v85, 1.0, v85
	v_rcp_f32_e32 v82, v82
	v_rcp_f32_e32 v83, v83
	v_rcp_f32_e32 v84, v84
	v_rcp_f32_e32 v85, v85
	v_pk_mul_f32 v[30:31], v[66:67], v[82:83]
	s_nop 0
	v_pk_mul_f32 v[26:27], v[26:27], v[30:31]
	v_pk_mul_f32 v[32:33], v[68:69], v[84:85]
	v_cvt_pk_bf16_f32 v26, v26, v27
	v_pk_mul_f32 v[28:29], v[28:29], v[32:33]
	s_nop 0
	v_cvt_pk_bf16_f32 v27, v28, v29
	global_store_dwordx2 v[92:93], v[26:27], off offset:8
	global_load_dwordx4 v[26:29], v[94:95], off offset:16
	s_nop 0
	global_load_dwordx4 v[30:33], v[58:59], off offset:16
	s_nop 0
	global_store_dwordx4 v[100:101], v[22:25], off offset:16
	s_waitcnt vmcnt(0)
	global_store_dwordx4 v[64:65], v[26:29], off offset:16
	v_pk_mul_f32 v[58:59], v[40:41], v[28:29]
	v_pk_mul_f32 v[66:67], v[38:39], v[26:27]
	v_pk_fma_f32 v[32:33], v[36:37], v[32:33], v[58:59]
	v_pk_fma_f32 v[30:31], v[34:35], v[30:31], v[66:67]
	v_pk_fma_f32 v[32:33], v[24:25], v[76:77], v[32:33]
	v_pk_fma_f32 v[30:31], v[22:23], v[74:75], v[30:31]
	v_pk_add_f32 v[32:33], v[80:81], v[32:33]
	v_pk_add_f32 v[30:31], v[78:79], v[30:31]
	v_mul_f32_e32 v66, 0xbfb8aa3b, v32
	v_mul_f32_e32 v58, 0xbfb8aa3b, v30
	v_mul_f32_e32 v59, 0xbfb8aa3b, v31
	v_mul_f32_e32 v67, 0xbfb8aa3b, v33
	v_exp_f32_e32 v58, v58
	v_exp_f32_e32 v59, v59
	v_exp_f32_e32 v66, v66
	v_exp_f32_e32 v67, v67
	v_add_f32_e32 v58, 1.0, v58
	v_add_f32_e32 v59, 1.0, v59
	v_add_f32_e32 v66, 1.0, v66
	v_add_f32_e32 v67, 1.0, v67
	v_rcp_f32_e32 v58, v58
	v_rcp_f32_e32 v59, v59
	v_rcp_f32_e32 v66, v66
	v_rcp_f32_e32 v67, v67
	v_pk_mul_f32 v[22:23], v[30:31], v[58:59]
	s_nop 0
	v_pk_mul_f32 v[18:19], v[18:19], v[22:23]
	v_pk_mul_f32 v[24:25], v[32:33], v[66:67]
	v_cvt_pk_bf16_f32 v18, v18, v19
	v_pk_mul_f32 v[20:21], v[20:21], v[24:25]
	s_nop 0
	v_cvt_pk_bf16_f32 v19, v20, v21
	global_store_dwordx2 v[60:61], v[18:19], off offset:8
	global_load_dwordx4 v[18:21], v[62:63], off offset:16
	s_nop 0
	global_load_dwordx4 v[22:25], v[50:51], off offset:16
	s_nop 0
	global_store_dwordx4 v[102:103], v[14:17], off offset:16
	s_waitcnt vmcnt(0)
	global_store_dwordx4 v[56:57], v[18:21], off offset:16
	v_pk_mul_f32 v[26:27], v[40:41], v[20:21]
	v_pk_mul_f32 v[28:29], v[38:39], v[18:19]
	v_pk_fma_f32 v[24:25], v[36:37], v[24:25], v[26:27]
	v_pk_fma_f32 v[22:23], v[34:35], v[22:23], v[28:29]
	v_pk_fma_f32 v[24:25], v[16:17], v[76:77], v[24:25]
	v_pk_fma_f32 v[22:23], v[14:15], v[74:75], v[22:23]
	v_pk_add_f32 v[24:25], v[80:81], v[24:25]
	v_pk_add_f32 v[22:23], v[78:79], v[22:23]
	v_mul_f32_e32 v28, 0xbfb8aa3b, v24
	v_mul_f32_e32 v26, 0xbfb8aa3b, v22
	v_mul_f32_e32 v27, 0xbfb8aa3b, v23
	v_mul_f32_e32 v29, 0xbfb8aa3b, v25
	v_exp_f32_e32 v26, v26
	v_exp_f32_e32 v27, v27
	v_exp_f32_e32 v28, v28
	v_exp_f32_e32 v29, v29
	v_add_f32_e32 v26, 1.0, v26
	v_add_f32_e32 v27, 1.0, v27
	v_add_f32_e32 v28, 1.0, v28
	v_add_f32_e32 v29, 1.0, v29
	v_rcp_f32_e32 v26, v26
	v_rcp_f32_e32 v27, v27
	v_rcp_f32_e32 v28, v28
	v_rcp_f32_e32 v29, v29
	v_pk_mul_f32 v[14:15], v[22:23], v[26:27]
	s_nop 0
	v_pk_mul_f32 v[10:11], v[10:11], v[14:15]
	v_pk_mul_f32 v[16:17], v[24:25], v[28:29]
	v_cvt_pk_bf16_f32 v10, v10, v11
	v_pk_mul_f32 v[12:13], v[12:13], v[16:17]
	s_nop 0
	v_cvt_pk_bf16_f32 v11, v12, v13
	global_store_dwordx2 v[52:53], v[10:11], off offset:8
	global_load_dwordx4 v[10:13], v[54:55], off offset:16
	s_nop 0
	global_load_dwordx4 v[14:17], v[42:43], off offset:16
	s_waitcnt vmcnt(0)
	v_pk_mul_f32 v[18:19], v[40:41], v[12:13]
	v_pk_mul_f32 v[20:21], v[38:39], v[10:11]
	v_pk_fma_f32 v[16:17], v[36:37], v[16:17], v[18:19]
	v_pk_fma_f32 v[14:15], v[34:35], v[14:15], v[20:21]
	v_pk_fma_f32 v[16:17], v[8:9], v[76:77], v[16:17]
	v_pk_fma_f32 v[14:15], v[6:7], v[74:75], v[14:15]
	v_pk_add_f32 v[16:17], v[80:81], v[16:17]
	v_pk_add_f32 v[14:15], v[78:79], v[14:15]
	v_mul_f32_e32 v20, 0xbfb8aa3b, v16
	v_mul_f32_e32 v18, 0xbfb8aa3b, v14
	v_mul_f32_e32 v19, 0xbfb8aa3b, v15
	v_mul_f32_e32 v21, 0xbfb8aa3b, v17
	v_exp_f32_e32 v18, v18
	v_exp_f32_e32 v19, v19
	v_exp_f32_e32 v20, v20
	v_exp_f32_e32 v21, v21
	v_add_f32_e32 v18, 1.0, v18
	v_add_f32_e32 v19, 1.0, v19
	v_add_f32_e32 v20, 1.0, v20
	v_add_f32_e32 v21, 1.0, v21
	v_rcp_f32_e32 v18, v18
	v_rcp_f32_e32 v19, v19
	v_rcp_f32_e32 v20, v20
	v_rcp_f32_e32 v21, v21
	global_store_dwordx4 v[48:49], v[10:13], off offset:16
	s_nop 1
	v_pk_mul_f32 v[10:11], v[14:15], v[18:19]
	v_pk_mul_f32 v[12:13], v[16:17], v[20:21]
	v_pk_mul_f32 v[2:3], v[2:3], v[10:11]
	v_pk_mul_f32 v[4:5], v[4:5], v[12:13]
	v_cvt_pk_bf16_f32 v2, v2, v3
	v_cvt_pk_bf16_f32 v3, v4, v5
	global_store_dwordx4 v[46:47], v[6:9], off offset:16
	global_store_dwordx2 v[44:45], v[2:3], off offset:8
	s_branch .LBB0_1082
